# NSA: fragment reads issued ahead of their MFMAs (S^T tile and P.V), block max by 16 v_max3; MoE gate_up row list via LDS-DMA table
# speedup vs baseline: 1.0196x; 1.0196x over previous
; #define LAS __attribute__((address_space(3)))
; #define MFMA32(a, b, c) __builtin_amdgcn_mfma_f32_32x32x16_bf16((a), (b), (c), 0, 0, 0)
; #define NSA_PRIO_ON(c) do { if ((c).hiw) __builtin_amdgcn_s_setprio(3); else __builtin_amdgcn_s_setprio(1); } while (0)
; #define NSA_PRIO_OFF() __builtin_amdgcn_s_setprio(0)
; template <int BR> __device__ __forceinline__ void nsa_s_tile(LAS unsigned char* L, int slot, const NsaBr& c, const bf16x8 (&qr)[4], f32x16 (&sa)[2]) {
;     NSA_PRIO_ON(c);
; #pragma unroll
;     for (int kt = 0; kt < 2; ++kt) {
; #pragma unroll
;         for (int i = 0; i < 16; ++i) sa[kt][i] = 0.f;
; #pragma unroll
;         for (int ks = 0; ks < 4; ++ks) { const bf16x8 a = *(const LAS bf16x8*)(L + slot + (32 * kt + c.r) * 144 + (16 * ks + 8 * c.h) * 2); sa[kt] = MFMA32(a, qr[ks], sa[kt]); }
;     }
;     NSA_PRIO_OFF();
; }
.LBB0_1771:
	v_add_u32_e32 v202, s10, v209
	ds_read_b128 v[66:69], v202
	ds_read_b128 v[86:89], v202 offset:32
	ds_read_b128 v[90:93], v202 offset:64
	ds_read_b128 v[94:97], v202 offset:96
	ds_read_b128 v[82:85], v202 offset:4608
	ds_read_b128 v[240:243], v202 offset:4640
	ds_read_b128 v[252:255], v202 offset:4672
	s_waitcnt lgkmcnt(6)
	v_mfma_f32_32x32x16_bf16 v[66:81], v[66:69], v[98:101], 0
	s_waitcnt lgkmcnt(5)
	v_mfma_f32_32x32x16_bf16 v[66:81], v[86:89], v[102:105], v[66:81]
	s_waitcnt lgkmcnt(4)
	v_mfma_f32_32x32x16_bf16 v[66:81], v[90:93], v[106:109], v[66:81]
	s_waitcnt lgkmcnt(3)
	v_mfma_f32_32x32x16_bf16 v[66:81], v[94:97], v[110:113], v[66:81]
	s_waitcnt lgkmcnt(2)
	v_mfma_f32_32x32x16_bf16 v[82:97], v[82:85], v[98:101], 0
	s_waitcnt lgkmcnt(1)
	v_mfma_f32_32x32x16_bf16 v[82:97], v[240:243], v[102:105], v[82:97]
	ds_read_b128 v[240:243], v202 offset:4704
	s_waitcnt lgkmcnt(1)
	v_mfma_f32_32x32x16_bf16 v[82:97], v[252:255], v[106:109], v[82:97]
	s_waitcnt lgkmcnt(0)
	v_mfma_f32_32x32x16_bf16 v[82:97], v[240:243], v[110:113], v[82:97]
	s_setprio 0
	s_cmp_eq_u32 s8, s31
	s_mov_b64 s[4:5], -1
	s_cbranch_scc0 .LBB0_1793

; #define LAS __attribute__((address_space(3)))
; #define LDS_BARRIER() do { asm volatile("s_waitcnt lgkmcnt(0)" ::: "memory"); __builtin_amdgcn_s_barrier(); asm volatile("" ::: "memory"); } while (0)
; #define MFMA32(a, b, c) __builtin_amdgcn_mfma_f32_32x32x16_bf16((a), (b), (c), 0, 0, 0)
; #define NSA_PRIO_ON(c) do { if ((c).hiw) __builtin_amdgcn_s_setprio(3); else __builtin_amdgcn_s_setprio(1); } while (0)
; #define NSA_PRIO_OFF() __builtin_amdgcn_s_setprio(0)
; template <int BR> __device__ __forceinline__ void nsa_softmax_pv(LAS unsigned char* L, int slot, const NsaBr& c, int j, f32x16 (&sa)[2], f32x16 (&oacc)[2], float& mrun, float& lrun) {
;     ...
;     const float msub = (BR == 1 && !mine) ? 1e30f : mrun;
;     f32x2 ps2 = {0.f, 0.f}; float nmsub = -msub; asm volatile("" : "+v"(nmsub)); const f32x2 nm2 = {nmsub, nmsub};
; #pragma unroll
;     for (int kt = 0; kt < 2; ++kt) {
; #pragma unroll
;         for (int i = 0; i < 16; i += 2) { const f32x2 x = (f32x2){sa[kt][i], sa[kt][i + 1]} + nm2; sa[kt][i] = __builtin_amdgcn_exp2f(x.x); sa[kt][i + 1] = __builtin_amdgcn_exp2f(x.y); }
; #pragma unroll
;         for (int i = 0; i < 16; i += 2) ps2 += (f32x2){sa[kt][i], sa[kt][i + 1]};
;     }
;     const float psum = ps2.x + ps2.y;
;     lrun += psum;
;     NSA_PRIO_ON(c);
; #pragma unroll
;     for (int kt = 0; kt < 2; ++kt)
; #pragma unroll
;         for (int s2 = 0; s2 < 2; ++s2) { const bf16x8 pf = pack_step(sa[kt], s2);
; #pragma unroll
;             for (int dt = 0; dt < 2; ++dt) { const LAS unsigned char* vp = L + slot + 9216 + (32 * dt + r) * 136 + (32 * kt + 16 * s2 + 4 * h) * 2;
;                 const s16x4 lo = *(const LAS s16x4*)vp, hi = *(const LAS s16x4*)(vp + 16);
;                 const bf16x8 vf = __builtin_shufflevector(lo, hi, 0, 1, 2, 3, 4, 5, 6, 7);
;                 oacc[dt] = MFMA32(vf, pf, oacc[dt]); } }
;     NSA_PRIO_OFF();
; }
; template <int BR> __device__ __forceinline__ void nsa_step(LAS unsigned char* L, const NsaBr& c, const bf16x8 (&qr)[4], int jj, int nblk, int s_cur, int s_nxt, int s_wr, ...
;     LDS_BARRIER();
;     if (jj + 2 < nblk) { nsa_kv_write(L, s_wr, c, kreg, vreg); if (jj + 3 < nblk) nsa_kv_load(c, c.jlo + jj + 3, kreg, vreg); }
.LBB0_1780:
	v_pk_add_f32 v[2:3], v[2:3], v[202:203] op_sel_hi:[1,0]
	v_pk_add_f32 v[4:5], v[4:5], v[202:203] op_sel_hi:[1,0]
	v_exp_f32_e32 v2, v2
	v_exp_f32_e32 v3, v3
	v_exp_f32_e32 v4, v4
	v_exp_f32_e32 v5, v5
	v_pk_add_f32 v[6:7], v[6:7], v[202:203] op_sel_hi:[1,0]
	v_pk_add_f32 v[8:9], v[8:9], v[202:203] op_sel_hi:[1,0]
	v_exp_f32_e32 v6, v6
	v_exp_f32_e32 v7, v7
	v_exp_f32_e32 v8, v8
	v_exp_f32_e32 v9, v9
	v_pk_add_f32 v[10:11], v[10:11], v[202:203] op_sel_hi:[1,0]
	v_pk_add_f32 v[12:13], v[12:13], v[202:203] op_sel_hi:[1,0]
	v_exp_f32_e32 v10, v10
	v_exp_f32_e32 v11, v11
	v_pk_add_f32 v[220:221], v[2:3], 0 op_sel_hi:[1,0]
	v_exp_f32_e32 v12, v12
	v_exp_f32_e32 v13, v13
	v_pk_add_f32 v[14:15], v[14:15], v[202:203] op_sel_hi:[1,0]
	v_pk_add_f32 v[220:221], v[4:5], v[220:221]
	v_exp_f32_e32 v14, v14
	v_exp_f32_e32 v15, v15
	v_pk_add_f32 v[16:17], v[16:17], v[202:203] op_sel_hi:[1,0]
	v_pk_add_f32 v[220:221], v[6:7], v[220:221]
	v_exp_f32_e32 v16, v16
	v_exp_f32_e32 v17, v17
	v_pk_add_f32 v[220:221], v[8:9], v[220:221]
	v_pk_add_f32 v[18:19], v[18:19], v[202:203] op_sel_hi:[1,0]
	v_pk_add_f32 v[220:221], v[10:11], v[220:221]
	v_exp_f32_e32 v18, v18
	v_exp_f32_e32 v19, v19
	v_pk_add_f32 v[20:21], v[20:21], v[202:203] op_sel_hi:[1,0]
	v_pk_add_f32 v[220:221], v[12:13], v[220:221]
	v_exp_f32_e32 v20, v20
	v_exp_f32_e32 v21, v21
	v_pk_add_f32 v[22:23], v[22:23], v[202:203] op_sel_hi:[1,0]
	v_pk_add_f32 v[220:221], v[14:15], v[220:221]
	v_exp_f32_e32 v22, v22
	v_exp_f32_e32 v23, v23
	v_pk_add_f32 v[24:25], v[24:25], v[202:203] op_sel_hi:[1,0]
	v_pk_add_f32 v[220:221], v[16:17], v[220:221]
	v_exp_f32_e32 v24, v24
	v_exp_f32_e32 v25, v25
	v_pk_add_f32 v[26:27], v[26:27], v[202:203] op_sel_hi:[1,0]
	v_pk_add_f32 v[28:29], v[28:29], v[202:203] op_sel_hi:[1,0]
	v_exp_f32_e32 v26, v26
	v_exp_f32_e32 v27, v27
	v_pk_add_f32 v[220:221], v[18:19], v[220:221]
	v_exp_f32_e32 v28, v28
	v_exp_f32_e32 v29, v29
	v_pk_add_f32 v[30:31], v[30:31], v[202:203] op_sel_hi:[1,0]
	v_pk_add_f32 v[220:221], v[20:21], v[220:221]
	v_exp_f32_e32 v30, v30
	v_exp_f32_e32 v31, v31
	v_pk_add_f32 v[32:33], v[32:33], v[202:203] op_sel_hi:[1,0]
	v_pk_add_f32 v[220:221], v[22:23], v[220:221]
	v_exp_f32_e32 v32, v32
	v_exp_f32_e32 v33, v33
	v_pk_add_f32 v[220:221], v[24:25], v[220:221]
	s_add_i32 s4, s30, 0
	v_pk_add_f32 v[220:221], v[26:27], v[220:221]
	v_cvt_pk_bf16_f32 v240, v2, v3
	v_cvt_pk_bf16_f32 v241, v4, v5
	v_cvt_pk_bf16_f32 v242, v6, v7
	v_cvt_pk_bf16_f32 v243, v8, v9
	s_nop 1
	v_add3_u32 v202, s4, v206, v210
	v_add_u32_e32 v219, 0x2000, v202
	v_add_u32_e32 v202, 0x3000, v202
	ds_read2_b64 v[244:247], v219 offset0:128 offset1:130
	ds_read2_b64 v[252:255], v202 offset0:160 offset1:162
	ds_read2_b64 v[6:9], v219 offset0:132 offset1:134
	s_nop 0
	v_pk_add_f32 v[220:221], v[28:29], v[220:221]
	s_nop 0
	v_pk_add_f32 v[220:221], v[30:31], v[220:221]
	s_nop 0
	v_pk_add_f32 v[220:221], v[32:33], v[220:221]
	s_nop 0
	v_add_f32_e32 v220, v220, v221
	v_add_f32_e32 v133, v133, v220
	s_waitcnt lgkmcnt(2)
	v_mfma_f32_32x32x16_bf16 v[34:49], v[244:247], v[240:243], v[34:49]
	s_waitcnt lgkmcnt(1)
	v_mfma_f32_32x32x16_bf16 v[50:65], v[252:255], v[240:243], v[50:65]
	v_cvt_pk_bf16_f32 v240, v10, v11
	v_cvt_pk_bf16_f32 v241, v12, v13
	v_cvt_pk_bf16_f32 v242, v14, v15
	v_cvt_pk_bf16_f32 v243, v16, v17
	s_nop 1
	ds_read2_b64 v[244:247], v202 offset0:164 offset1:166
	ds_read2_b64 v[252:255], v219 offset0:136 offset1:138
	ds_read2_b64 v[10:13], v202 offset0:168 offset1:170
	s_waitcnt lgkmcnt(3)
	v_mfma_f32_32x32x16_bf16 v[34:49], v[6:9], v[240:243], v[34:49]
	s_waitcnt lgkmcnt(2)
	v_mfma_f32_32x32x16_bf16 v[50:65], v[244:247], v[240:243], v[50:65]
	v_cvt_pk_bf16_f32 v240, v18, v19
	v_cvt_pk_bf16_f32 v241, v20, v21
	v_cvt_pk_bf16_f32 v242, v22, v23
	v_cvt_pk_bf16_f32 v243, v24, v25
	s_nop 1
	ds_read2_b64 v[6:9], v219 offset0:140 offset1:142
	ds_read2_b64 v[244:247], v202 offset0:172 offset1:174
	s_waitcnt lgkmcnt(3)
	v_mfma_f32_32x32x16_bf16 v[34:49], v[252:255], v[240:243], v[34:49]
	s_waitcnt lgkmcnt(2)
	v_mfma_f32_32x32x16_bf16 v[50:65], v[10:13], v[240:243], v[50:65]
	v_cvt_pk_bf16_f32 v240, v26, v27
	v_cvt_pk_bf16_f32 v241, v28, v29
	v_cvt_pk_bf16_f32 v242, v30, v31
	v_cvt_pk_bf16_f32 v243, v32, v33
	s_nop 1
	s_waitcnt lgkmcnt(1)
	v_mfma_f32_32x32x16_bf16 v[34:49], v[6:9], v[240:243], v[34:49]
	s_waitcnt lgkmcnt(0)
	v_mfma_f32_32x32x16_bf16 v[50:65], v[244:247], v[240:243], v[50:65]
	s_setprio 0
	s_andn2_b64 vcc, exec, s[26:27]
	s_cbranch_vccnz .LBB0_1803
	s_waitcnt lgkmcnt(0)
	s_barrier
	s_add_i32 s5, s31, 3
	s_cmp_gt_u32 s5, s8
	s_cbranch_scc1 .LBB0_1784
	v_add3_u32 v202, s4, v207, v198
	s_waitcnt vmcnt(1)
	ds_write_b128 v202, v[114:117]
	v_add_u32_e32 v202, s4, v208
	s_add_i32 s4, s31, 4
	v_add3_u32 v202, v202, v198, s13
	s_cmp_gt_u32 s4, s8
	s_waitcnt vmcnt(0)
	ds_write2_b64 v202, v[118:119], v[120:121] offset1:1
	s_cbranch_scc1 .LBB0_1784
	v_lshl_add_u64 v[114:115], v[196:197], 0, v[198:199]
	v_add_co_u32_e32 v114, vcc, 0x6e008000, v114
	v_lshl_add_u64 v[118:119], v[200:201], 0, v[198:199]
	s_nop 0
	v_addc_co_u32_e32 v115, vcc, 0, v115, vcc
	v_add_co_u32_e32 v118, vcc, 0x6e400000, v118
	global_load_dwordx4 v[114:117], v[114:115], off
	s_nop 0
	v_addc_co_u32_e32 v119, vcc, 0, v119, vcc
	global_load_dwordx4 v[118:121], v[118:119], off offset:512

; #define LAS __attribute__((address_space(3)))
; #define MFMA32(a, b, c) __builtin_amdgcn_mfma_f32_32x32x16_bf16((a), (b), (c), 0, 0, 0)
; #define NSA_PRIO_ON(c) do { if ((c).hiw) __builtin_amdgcn_s_setprio(3); else __builtin_amdgcn_s_setprio(1); } while (0)
; #define NSA_PRIO_OFF() __builtin_amdgcn_s_setprio(0)
; template <int BR> __device__ __forceinline__ void nsa_s_tile(LAS unsigned char* L, int slot, const NsaBr& c, const bf16x8 (&qr)[4], f32x16 (&sa)[2]) {
;     NSA_PRIO_ON(c);
; #pragma unroll
;     for (int kt = 0; kt < 2; ++kt) {
; #pragma unroll
;         for (int i = 0; i < 16; ++i) sa[kt][i] = 0.f;
; #pragma unroll
;         for (int ks = 0; ks < 4; ++ks) { const bf16x8 a = *(const LAS bf16x8*)(L + slot + (32 * kt + c.r) * 144 + (16 * ks + 8 * c.h) * 2); sa[kt] = MFMA32(a, qr[ks], sa[kt]); }
;     }
;     NSA_PRIO_OFF();
; }
; template <int BR> __device__ __forceinline__ void nsa_softmax_pv(LAS unsigned char* L, int slot, const NsaBr& c, int j, f32x16 (&sa)[2], f32x16 (&oacc)[2], float& mrun, float& lrun) {
;     const int h = c.h, r = c.r, t = c.t;
;     const bool mine = BR == 1 ? ((c.selmask >> j) & 1u) != 0u : true;
;     float mblk = -1e30f;
;     const bool edge = (j == c.qt) || (BR == 2 && c.qt >= 8 && j == c.jlo);
;     if (edge) {
; #pragma unroll
;         for (int kt = 0; kt < 2; ++kt)
; #pragma unroll
;             for (int i = 0; i < 16; ++i) { const int key = 64 * j + 32 * kt + (i & 3) + 8 * (i >> 2) + 4 * h;
;                 int pb = (t - key) >> 31;
;                 if (BR == 2) pb |= (key - (t - 511)) >> 31;
;                 const float v = sa[kt][i] + __int_as_float(pb & (int)0xF149F2CA); sa[kt][i] = v; mblk = fmaxf(mblk, v); }
;     } else {
; #pragma unroll
;         for (int kt = 0; kt < 2; ++kt)
; #pragma unroll
;             for (int i = 0; i < 16; i += 2) mblk = fmaxf(mblk, fmaxf(sa[kt][i], sa[kt][i + 1]));
;     }
.LBB0_1789:
	v_add_u32_e32 v202, s3, v209
	ds_read_b128 v[2:5], v202
	ds_read_b128 v[22:25], v202 offset:32
	ds_read_b128 v[26:29], v202 offset:64
	ds_read_b128 v[30:33], v202 offset:96
	ds_read_b128 v[18:21], v202 offset:4608
	ds_read_b128 v[240:243], v202 offset:4640
	ds_read_b128 v[252:255], v202 offset:4672
	s_waitcnt lgkmcnt(6)
	v_mfma_f32_32x32x16_bf16 v[2:17], v[2:5], v[98:101], 0
	s_waitcnt lgkmcnt(5)
	v_mfma_f32_32x32x16_bf16 v[2:17], v[22:25], v[102:105], v[2:17]
	s_waitcnt lgkmcnt(4)
	v_mfma_f32_32x32x16_bf16 v[2:17], v[26:29], v[106:109], v[2:17]
	s_waitcnt lgkmcnt(3)
	v_mfma_f32_32x32x16_bf16 v[2:17], v[30:33], v[110:113], v[2:17]
	s_waitcnt lgkmcnt(2)
	v_mfma_f32_32x32x16_bf16 v[18:33], v[18:21], v[98:101], 0
	s_waitcnt lgkmcnt(1)
	v_mfma_f32_32x32x16_bf16 v[18:33], v[240:243], v[102:105], v[18:33]
	ds_read_b128 v[240:243], v202 offset:4704
	s_waitcnt lgkmcnt(1)
	v_mfma_f32_32x32x16_bf16 v[18:33], v[252:255], v[106:109], v[18:33]
	s_waitcnt lgkmcnt(0)
	v_mfma_f32_32x32x16_bf16 v[18:33], v[240:243], v[110:113], v[18:33]
	s_setprio 0
.LBB0_1790:
	v_xor_b32_e32 v202, 0x80000000, v218
	s_cmp_eq_u32 s11, s31
	s_mov_b64 s[4:5], -1
	s_cbranch_scc1 .LBB0_1794
	v_max3_f32 v219, v66, s12, v67
	v_max3_f32 v219, v219, v68, v69
	v_max3_f32 v219, v219, v70, v71
	v_max3_f32 v219, v219, v72, v73
	v_max3_f32 v219, v219, v74, v75
	v_max3_f32 v219, v219, v76, v77
	v_max3_f32 v219, v219, v78, v79
	v_max3_f32 v219, v219, v80, v81
	v_max3_f32 v219, v219, v82, v83
	v_max3_f32 v219, v219, v84, v85
	v_max3_f32 v219, v219, v86, v87
	v_max3_f32 v219, v219, v88, v89
	v_max3_f32 v219, v219, v90, v91
	v_max3_f32 v219, v219, v92, v93
	v_max3_f32 v219, v219, v94, v95
	v_max3_f32 v219, v219, v96, v97
	s_cbranch_execz .LBB0_1795
	s_branch .LBB0_1796

; template <int BR> __device__ __forceinline__ void nsa_softmax_pv(LAS unsigned char* L, int slot, const NsaBr& c, int j, f32x16 (&sa)[2], f32x16 (&oacc)[2], float& mrun, float& lrun) {
;     ...
; #pragma unroll
;         for (int kt = 0; kt < 2; ++kt)
; #pragma unroll
;             for (int i = 0; i < 16; i += 2) mblk = fmaxf(mblk, fmaxf(sa[kt][i], sa[kt][i + 1]));
;     }
.LBB0_1793:
	v_max3_f32 v202, v2, s12, v3
	v_max3_f32 v202, v202, v4, v5
	v_max3_f32 v202, v202, v6, v7
	v_max3_f32 v202, v202, v8, v9
	v_max3_f32 v202, v202, v10, v11
	v_max3_f32 v202, v202, v12, v13
	v_max3_f32 v202, v202, v14, v15
	v_max3_f32 v202, v202, v16, v17
	v_max3_f32 v202, v202, v18, v19
	v_max3_f32 v202, v202, v20, v21
	v_max3_f32 v202, v202, v22, v23
	v_max3_f32 v202, v202, v24, v25
	v_max3_f32 v202, v202, v26, v27
	v_max3_f32 v202, v202, v28, v29
	v_max3_f32 v202, v202, v30, v31
	v_max3_f32 v202, v202, v32, v33
	s_cbranch_execz .LBB0_1773
	s_branch .LBB0_1774

; #define LAS __attribute__((address_space(3)))
; #define MFMA32(a, b, c) __builtin_amdgcn_mfma_f32_32x32x16_bf16((a), (b), (c), 0, 0, 0)
; #define NSA_PRIO_ON(c) do { if ((c).hiw) __builtin_amdgcn_s_setprio(3); else __builtin_amdgcn_s_setprio(1); } while (0)
; #define NSA_PRIO_OFF() __builtin_amdgcn_s_setprio(0)
; template <int BR> __device__ __forceinline__ void nsa_softmax_pv(LAS unsigned char* L, int slot, const NsaBr& c, int j, f32x16 (&sa)[2], f32x16 (&oacc)[2], float& mrun, float& lrun) {
;     ...
;     const float msub = (BR == 1 && !mine) ? 1e30f : mrun;
;     f32x2 ps2 = {0.f, 0.f}; float nmsub = -msub; asm volatile("" : "+v"(nmsub)); const f32x2 nm2 = {nmsub, nmsub};
; #pragma unroll
;     for (int kt = 0; kt < 2; ++kt) {
; #pragma unroll
;         for (int i = 0; i < 16; i += 2) { const f32x2 x = (f32x2){sa[kt][i], sa[kt][i + 1]} + nm2; sa[kt][i] = __builtin_amdgcn_exp2f(x.x); sa[kt][i + 1] = __builtin_amdgcn_exp2f(x.y); }
; #pragma unroll
;         for (int i = 0; i < 16; i += 2) ps2 += (f32x2){sa[kt][i], sa[kt][i + 1]};
;     }
;     const float psum = ps2.x + ps2.y;
;     lrun += psum;
;     NSA_PRIO_ON(c);
; #pragma unroll
;     for (int kt = 0; kt < 2; ++kt)
; #pragma unroll
;         for (int s2 = 0; s2 < 2; ++s2) { const bf16x8 pf = pack_step(sa[kt], s2);
; #pragma unroll
;             for (int dt = 0; dt < 2; ++dt) { const LAS unsigned char* vp = L + slot + 9216 + (32 * dt + r) * 136 + (32 * kt + 16 * s2 + 4 * h) * 2;
;                 const s16x4 lo = *(const LAS s16x4*)vp, hi = *(const LAS s16x4*)(vp + 16);
;                 const bf16x8 vf = __builtin_shufflevector(lo, hi, 0, 1, 2, 3, 4, 5, 6, 7);
;                 oacc[dt] = MFMA32(vf, pf, oacc[dt]); } }
;     NSA_PRIO_OFF();
.LBB0_1802:
	v_pk_add_f32 v[66:67], v[66:67], v[202:203] op_sel_hi:[1,0]
	v_pk_add_f32 v[68:69], v[68:69], v[202:203] op_sel_hi:[1,0]
	v_exp_f32_e32 v66, v66
	v_exp_f32_e32 v67, v67
	v_exp_f32_e32 v68, v68
	v_exp_f32_e32 v69, v69
	v_pk_add_f32 v[70:71], v[70:71], v[202:203] op_sel_hi:[1,0]
	v_pk_add_f32 v[72:73], v[72:73], v[202:203] op_sel_hi:[1,0]
	v_exp_f32_e32 v70, v70
	v_exp_f32_e32 v71, v71
	v_exp_f32_e32 v72, v72
	v_exp_f32_e32 v73, v73
	v_pk_add_f32 v[74:75], v[74:75], v[202:203] op_sel_hi:[1,0]
	v_pk_add_f32 v[76:77], v[76:77], v[202:203] op_sel_hi:[1,0]
	v_exp_f32_e32 v74, v74
	v_exp_f32_e32 v75, v75
	v_pk_add_f32 v[220:221], v[66:67], 0 op_sel_hi:[1,0]
	v_exp_f32_e32 v76, v76
	v_exp_f32_e32 v77, v77
	v_pk_add_f32 v[78:79], v[78:79], v[202:203] op_sel_hi:[1,0]
	v_pk_add_f32 v[220:221], v[68:69], v[220:221]
	v_exp_f32_e32 v78, v78
	v_exp_f32_e32 v79, v79
	v_pk_add_f32 v[80:81], v[80:81], v[202:203] op_sel_hi:[1,0]
	v_pk_add_f32 v[220:221], v[70:71], v[220:221]
	v_exp_f32_e32 v80, v80
	v_exp_f32_e32 v81, v81
	v_pk_add_f32 v[220:221], v[72:73], v[220:221]
	v_pk_add_f32 v[82:83], v[82:83], v[202:203] op_sel_hi:[1,0]
	v_pk_add_f32 v[220:221], v[74:75], v[220:221]
	v_exp_f32_e32 v82, v82
	v_exp_f32_e32 v83, v83
	v_pk_add_f32 v[84:85], v[84:85], v[202:203] op_sel_hi:[1,0]
	v_pk_add_f32 v[220:221], v[76:77], v[220:221]
	v_exp_f32_e32 v84, v84
	v_exp_f32_e32 v85, v85
	v_pk_add_f32 v[86:87], v[86:87], v[202:203] op_sel_hi:[1,0]
	v_pk_add_f32 v[220:221], v[78:79], v[220:221]
	v_exp_f32_e32 v86, v86
	v_exp_f32_e32 v87, v87
	v_pk_add_f32 v[88:89], v[88:89], v[202:203] op_sel_hi:[1,0]
	v_pk_add_f32 v[220:221], v[80:81], v[220:221]
	v_exp_f32_e32 v88, v88
	v_exp_f32_e32 v89, v89
	v_pk_add_f32 v[90:91], v[90:91], v[202:203] op_sel_hi:[1,0]
	v_pk_add_f32 v[92:93], v[92:93], v[202:203] op_sel_hi:[1,0]
	v_exp_f32_e32 v90, v90
	v_exp_f32_e32 v91, v91
	v_pk_add_f32 v[220:221], v[82:83], v[220:221]
	v_exp_f32_e32 v92, v92
	v_exp_f32_e32 v93, v93
	v_pk_add_f32 v[94:95], v[94:95], v[202:203] op_sel_hi:[1,0]
	v_pk_add_f32 v[220:221], v[84:85], v[220:221]
	v_exp_f32_e32 v94, v94
	v_exp_f32_e32 v95, v95
	v_pk_add_f32 v[96:97], v[96:97], v[202:203] op_sel_hi:[1,0]
	v_pk_add_f32 v[220:221], v[86:87], v[220:221]
	v_exp_f32_e32 v96, v96
	v_exp_f32_e32 v97, v97
	v_pk_add_f32 v[220:221], v[88:89], v[220:221]
	v_cvt_pk_bf16_f32 v240, v66, v67
	v_cvt_pk_bf16_f32 v241, v68, v69
	v_cvt_pk_bf16_f32 v242, v70, v71
	v_cvt_pk_bf16_f32 v243, v72, v73
	s_nop 1
	v_add_u32_e32 v202, s10, v211
	v_add_u32_e32 v219, 0x2000, v202
	v_add_u32_e32 v202, 0x3000, v202
	ds_read2_b64 v[244:247], v219 offset0:128 offset1:130
	ds_read2_b64 v[252:255], v202 offset0:160 offset1:162
	ds_read2_b64 v[70:73], v219 offset0:132 offset1:134
	s_nop 0
	v_pk_add_f32 v[220:221], v[90:91], v[220:221]
	s_nop 0
	v_pk_add_f32 v[220:221], v[92:93], v[220:221]
	s_nop 0
	v_pk_add_f32 v[220:221], v[94:95], v[220:221]
	s_nop 0
	v_pk_add_f32 v[220:221], v[96:97], v[220:221]
	s_nop 0
	v_add_f32_e32 v220, v220, v221
	v_add_f32_e32 v133, v133, v220
	s_waitcnt lgkmcnt(2)
	v_mfma_f32_32x32x16_bf16 v[34:49], v[244:247], v[240:243], v[34:49]
	s_waitcnt lgkmcnt(1)
	v_mfma_f32_32x32x16_bf16 v[50:65], v[252:255], v[240:243], v[50:65]
	v_cvt_pk_bf16_f32 v240, v74, v75
	v_cvt_pk_bf16_f32 v241, v76, v77
	v_cvt_pk_bf16_f32 v242, v78, v79
	v_cvt_pk_bf16_f32 v243, v80, v81
	s_nop 1
	ds_read2_b64 v[244:247], v202 offset0:164 offset1:166
	ds_read2_b64 v[252:255], v219 offset0:136 offset1:138
	ds_read2_b64 v[74:77], v202 offset0:168 offset1:170
	s_waitcnt lgkmcnt(3)
	v_mfma_f32_32x32x16_bf16 v[34:49], v[70:73], v[240:243], v[34:49]
	s_waitcnt lgkmcnt(2)
	v_mfma_f32_32x32x16_bf16 v[50:65], v[244:247], v[240:243], v[50:65]
	v_cvt_pk_bf16_f32 v240, v82, v83
	v_cvt_pk_bf16_f32 v241, v84, v85
	v_cvt_pk_bf16_f32 v242, v86, v87
	v_cvt_pk_bf16_f32 v243, v88, v89
	s_nop 1
	ds_read2_b64 v[70:73], v219 offset0:140 offset1:142
	ds_read2_b64 v[244:247], v202 offset0:172 offset1:174
	s_waitcnt lgkmcnt(3)
	v_mfma_f32_32x32x16_bf16 v[34:49], v[252:255], v[240:243], v[34:49]
	s_waitcnt lgkmcnt(2)
	v_mfma_f32_32x32x16_bf16 v[50:65], v[74:77], v[240:243], v[50:65]
	v_cvt_pk_bf16_f32 v240, v90, v91
	v_cvt_pk_bf16_f32 v241, v92, v93
	v_cvt_pk_bf16_f32 v242, v94, v95
	v_cvt_pk_bf16_f32 v243, v96, v97
	s_nop 1
	s_waitcnt lgkmcnt(1)
	v_mfma_f32_32x32x16_bf16 v[34:49], v[70:73], v[240:243], v[34:49]
	s_waitcnt lgkmcnt(0)
	v_mfma_f32_32x32x16_bf16 v[50:65], v[244:247], v[240:243], v[50:65]
	s_setprio 0

; #define LAS __attribute__((address_space(3)))
; #define MFMA32(a, b, c) __builtin_amdgcn_mfma_f32_32x32x16_bf16((a), (b), (c), 0, 0, 0)
; #define NSA_PRIO_ON(c) do { if ((c).hiw) __builtin_amdgcn_s_setprio(3); else __builtin_amdgcn_s_setprio(1); } while (0)
; #define NSA_PRIO_OFF() __builtin_amdgcn_s_setprio(0)
; template <int BR> __device__ __forceinline__ void nsa_s_tile(LAS unsigned char* L, int slot, const NsaBr& c, const bf16x8 (&qr)[4], f32x16 (&sa)[2]) {
;     NSA_PRIO_ON(c);
; #pragma unroll
;     for (int kt = 0; kt < 2; ++kt) {
; #pragma unroll
;         for (int i = 0; i < 16; ++i) sa[kt][i] = 0.f;
; #pragma unroll
;         for (int ks = 0; ks < 4; ++ks) { const bf16x8 a = *(const LAS bf16x8*)(L + slot + (32 * kt + c.r) * 144 + (16 * ks + 8 * c.h) * 2); sa[kt] = MFMA32(a, qr[ks], sa[kt]); }
;     }
;     NSA_PRIO_OFF();
; }
; template <int BR> __device__ __forceinline__ void nsa_softmax_pv(LAS unsigned char* L, int slot, const NsaBr& c, int j, f32x16 (&sa)[2], f32x16 (&oacc)[2], float& mrun, float& lrun) {
;     const int h = c.h, r = c.r, t = c.t;
;     const bool mine = BR == 1 ? ((c.selmask >> j) & 1u) != 0u : true;
;     float mblk = -1e30f;
;     const bool edge = (j == c.qt) || (BR == 2 && c.qt >= 8 && j == c.jlo);
;     if (edge) {
; #pragma unroll
;         for (int kt = 0; kt < 2; ++kt)
; #pragma unroll
;             for (int i = 0; i < 16; ++i) { const int key = 64 * j + 32 * kt + (i & 3) + 8 * (i >> 2) + 4 * h;
;                 int pb = (t - key) >> 31;
;                 if (BR == 2) pb |= (key - (t - 511)) >> 31;
;                 const float v = sa[kt][i] + __int_as_float(pb & (int)0xF149F2CA); sa[kt][i] = v; mblk = fmaxf(mblk, v); }
;     } else {
; #pragma unroll
;         for (int kt = 0; kt < 2; ++kt)
; #pragma unroll
;             for (int i = 0; i < 16; i += 2) mblk = fmaxf(mblk, fmaxf(sa[kt][i], sa[kt][i + 1]));
;     }
.LBB0_1823:
	v_add_u32_e32 v122, s50, v209
	ds_read_b128 v[66:69], v122
	ds_read_b128 v[86:89], v122 offset:32
	ds_read_b128 v[90:93], v122 offset:64
	ds_read_b128 v[94:97], v122 offset:96
	ds_read_b128 v[82:85], v122 offset:4608
	ds_read_b128 v[176:179], v122 offset:4640
	ds_read_b128 v[252:255], v122 offset:4672
	s_waitcnt lgkmcnt(6)
	v_mfma_f32_32x32x16_bf16 v[66:81], v[66:69], v[98:101], 0
	s_waitcnt lgkmcnt(5)
	v_mfma_f32_32x32x16_bf16 v[66:81], v[86:89], v[102:105], v[66:81]
	s_waitcnt lgkmcnt(4)
	v_mfma_f32_32x32x16_bf16 v[66:81], v[90:93], v[106:109], v[66:81]
	s_waitcnt lgkmcnt(3)
	v_mfma_f32_32x32x16_bf16 v[66:81], v[94:97], v[110:113], v[66:81]
	s_waitcnt lgkmcnt(2)
	v_mfma_f32_32x32x16_bf16 v[82:97], v[82:85], v[98:101], 0
	s_waitcnt lgkmcnt(1)
	v_mfma_f32_32x32x16_bf16 v[82:97], v[176:179], v[102:105], v[82:97]
	ds_read_b128 v[176:179], v122 offset:4704
	s_waitcnt lgkmcnt(1)
	v_mfma_f32_32x32x16_bf16 v[82:97], v[252:255], v[106:109], v[82:97]
	s_waitcnt lgkmcnt(0)
	v_mfma_f32_32x32x16_bf16 v[82:97], v[176:179], v[110:113], v[82:97]
	s_setprio 0
.LBB0_1824:
	s_cmp_eq_u32 s8, s4
	s_cselect_b64 s[0:1], -1, 0
	s_cmp_eq_u32 s4, 0
	s_cselect_b64 s[30:31], -1, 0
	s_and_b64 s[30:31], s[14:15], s[30:31]
	s_or_b64 s[30:31], s[0:1], s[30:31]
	s_mov_b64 s[0:1], -1
	s_and_b64 vcc, exec, s[30:31]
	s_cbranch_vccnz .LBB0_1826
	v_max3_f32 v122, v34, s12, v35
	v_max3_f32 v122, v122, v36, v37
	v_max3_f32 v122, v122, v38, v39
	v_max3_f32 v122, v122, v40, v41
	v_max3_f32 v122, v122, v42, v43
	v_max3_f32 v122, v122, v44, v45
	v_max3_f32 v122, v122, v46, v47
	v_max3_f32 v122, v122, v48, v49
	v_max3_f32 v122, v122, v50, v51
	v_max3_f32 v122, v122, v52, v53
	v_max3_f32 v122, v122, v54, v55
	v_max3_f32 v122, v122, v56, v57
	v_max3_f32 v122, v122, v58, v59
	v_max3_f32 v122, v122, v60, v61
	v_max3_f32 v122, v122, v62, v63
	v_max3_f32 v122, v122, v64, v65
	s_mov_b64 s[0:1], 0

; #define LAS __attribute__((address_space(3)))
; #define LDS_BARRIER() do { asm volatile("s_waitcnt lgkmcnt(0)" ::: "memory"); __builtin_amdgcn_s_barrier(); asm volatile("" ::: "memory"); } while (0)
; #define MFMA32(a, b, c) __builtin_amdgcn_mfma_f32_32x32x16_bf16((a), (b), (c), 0, 0, 0)
; #define NSA_PRIO_ON(c) do { if ((c).hiw) __builtin_amdgcn_s_setprio(3); else __builtin_amdgcn_s_setprio(1); } while (0)
; #define NSA_PRIO_OFF() __builtin_amdgcn_s_setprio(0)
; template <int BR> __device__ __forceinline__ void nsa_softmax_pv(LAS unsigned char* L, int slot, const NsaBr& c, int j, f32x16 (&sa)[2], f32x16 (&oacc)[2], float& mrun, float& lrun) {
;     ...
;     const float msub = (BR == 1 && !mine) ? 1e30f : mrun;
;     f32x2 ps2 = {0.f, 0.f}; float nmsub = -msub; asm volatile("" : "+v"(nmsub)); const f32x2 nm2 = {nmsub, nmsub};
; #pragma unroll
;     for (int kt = 0; kt < 2; ++kt) {
; #pragma unroll
;         for (int i = 0; i < 16; i += 2) { const f32x2 x = (f32x2){sa[kt][i], sa[kt][i + 1]} + nm2; sa[kt][i] = __builtin_amdgcn_exp2f(x.x); sa[kt][i + 1] = __builtin_amdgcn_exp2f(x.y); }
; #pragma unroll
;         for (int i = 0; i < 16; i += 2) ps2 += (f32x2){sa[kt][i], sa[kt][i + 1]};
;     }
;     const float psum = ps2.x + ps2.y;
;     lrun += psum;
;     NSA_PRIO_ON(c);
; #pragma unroll
;     for (int kt = 0; kt < 2; ++kt)
; #pragma unroll
;         for (int s2 = 0; s2 < 2; ++s2) { const bf16x8 pf = pack_step(sa[kt], s2);
; #pragma unroll
;             for (int dt = 0; dt < 2; ++dt) { const LAS unsigned char* vp = L + slot + 9216 + (32 * dt + r) * 136 + (32 * kt + 16 * s2 + 4 * h) * 2;
;                 const s16x4 lo = *(const LAS s16x4*)vp, hi = *(const LAS s16x4*)(vp + 16);
;                 const bf16x8 vf = __builtin_shufflevector(lo, hi, 0, 1, 2, 3, 4, 5, 6, 7);
;                 oacc[dt] = MFMA32(vf, pf, oacc[dt]); } }
;     NSA_PRIO_OFF();
; }
; template <int BR> __device__ __forceinline__ void nsa_step(LAS unsigned char* L, const NsaBr& c, const bf16x8 (&qr)[4], int jj, int nblk, int s_cur, int s_nxt, int s_wr, ...
;     LDS_BARRIER();
;     if (jj + 2 < nblk) { nsa_kv_write(L, s_wr, c, kreg, vreg); if (jj + 3 < nblk) nsa_kv_load(c, c.jlo + jj + 3, kreg, vreg); }
.LBB0_1834:
	v_pk_add_f32 v[34:35], v[34:35], v[138:139] op_sel_hi:[1,0]
	v_pk_add_f32 v[36:37], v[36:37], v[138:139] op_sel_hi:[1,0]
	v_exp_f32_e32 v34, v34
	v_exp_f32_e32 v35, v35
	v_exp_f32_e32 v36, v36
	v_exp_f32_e32 v37, v37
	v_pk_add_f32 v[38:39], v[38:39], v[138:139] op_sel_hi:[1,0]
	v_pk_add_f32 v[40:41], v[40:41], v[138:139] op_sel_hi:[1,0]
	v_exp_f32_e32 v38, v38
	v_exp_f32_e32 v39, v39
	v_exp_f32_e32 v40, v40
	v_exp_f32_e32 v41, v41
	v_pk_add_f32 v[42:43], v[42:43], v[138:139] op_sel_hi:[1,0]
	v_pk_add_f32 v[44:45], v[44:45], v[138:139] op_sel_hi:[1,0]
	v_exp_f32_e32 v42, v42
	v_exp_f32_e32 v43, v43
	v_pk_add_f32 v[176:177], v[34:35], 0 op_sel_hi:[1,0]
	v_exp_f32_e32 v44, v44
	v_exp_f32_e32 v45, v45
	v_pk_add_f32 v[46:47], v[46:47], v[138:139] op_sel_hi:[1,0]
	v_pk_add_f32 v[176:177], v[36:37], v[176:177]
	v_exp_f32_e32 v46, v46
	v_exp_f32_e32 v47, v47
	v_pk_add_f32 v[48:49], v[48:49], v[138:139] op_sel_hi:[1,0]
	v_pk_add_f32 v[176:177], v[38:39], v[176:177]
	v_exp_f32_e32 v48, v48
	v_exp_f32_e32 v49, v49
	v_pk_add_f32 v[176:177], v[40:41], v[176:177]
	v_pk_add_f32 v[50:51], v[50:51], v[138:139] op_sel_hi:[1,0]
	v_pk_add_f32 v[176:177], v[42:43], v[176:177]
	v_exp_f32_e32 v50, v50
	v_exp_f32_e32 v51, v51
	v_pk_add_f32 v[52:53], v[52:53], v[138:139] op_sel_hi:[1,0]
	v_pk_add_f32 v[176:177], v[44:45], v[176:177]
	v_exp_f32_e32 v52, v52
	v_exp_f32_e32 v53, v53
	v_pk_add_f32 v[54:55], v[54:55], v[138:139] op_sel_hi:[1,0]
	v_pk_add_f32 v[176:177], v[46:47], v[176:177]
	v_exp_f32_e32 v54, v54
	v_exp_f32_e32 v55, v55
	v_pk_add_f32 v[56:57], v[56:57], v[138:139] op_sel_hi:[1,0]
	v_pk_add_f32 v[176:177], v[48:49], v[176:177]
	v_exp_f32_e32 v56, v56
	v_exp_f32_e32 v57, v57
	v_pk_add_f32 v[58:59], v[58:59], v[138:139] op_sel_hi:[1,0]
	v_pk_add_f32 v[60:61], v[60:61], v[138:139] op_sel_hi:[1,0]
	v_exp_f32_e32 v58, v58
	v_exp_f32_e32 v59, v59
	v_pk_add_f32 v[176:177], v[50:51], v[176:177]
	v_exp_f32_e32 v60, v60
	v_exp_f32_e32 v61, v61
	v_pk_add_f32 v[62:63], v[62:63], v[138:139] op_sel_hi:[1,0]
	v_pk_add_f32 v[176:177], v[52:53], v[176:177]
	v_exp_f32_e32 v62, v62
	v_exp_f32_e32 v63, v63
	v_pk_add_f32 v[64:65], v[64:65], v[138:139] op_sel_hi:[1,0]
	v_pk_add_f32 v[176:177], v[54:55], v[176:177]
	v_exp_f32_e32 v64, v64
	v_exp_f32_e32 v65, v65
	v_pk_add_f32 v[176:177], v[56:57], v[176:177]
	s_add_i32 s0, s7, 0
	v_pk_add_f32 v[176:177], v[58:59], v[176:177]
	s_nop 0
	v_pk_add_f32 v[176:177], v[60:61], v[176:177]
	s_nop 0
	v_pk_add_f32 v[176:177], v[62:63], v[176:177]
	s_nop 0
	v_pk_add_f32 v[176:177], v[64:65], v[176:177]
	s_nop 0
	v_add_f32_e32 v138, v176, v177
	v_add_f32_e32 v155, v155, v138
	v_add3_u32 v138, s0, v206, v210
	v_add_u32_e32 v175, 0x2000, v138
	v_cvt_pk_bf16_f32 v176, v34, v35
	v_cvt_pk_bf16_f32 v177, v36, v37
	v_cvt_pk_bf16_f32 v178, v38, v39
	v_cvt_pk_bf16_f32 v179, v40, v41
	s_nop 1
	v_add_u32_e32 v138, 0x3000, v138
	ds_read2_b64 v[180:183], v175 offset0:128 offset1:130
	ds_read2_b64 v[252:255], v138 offset0:160 offset1:162
	ds_read2_b64 v[38:41], v175 offset0:132 offset1:134
	s_waitcnt lgkmcnt(2)
	v_mfma_f32_32x32x16_bf16 v[2:17], v[180:183], v[176:179], v[2:17]
	s_waitcnt lgkmcnt(1)
	v_mfma_f32_32x32x16_bf16 v[18:33], v[252:255], v[176:179], v[18:33]
	v_cvt_pk_bf16_f32 v176, v42, v43
	v_cvt_pk_bf16_f32 v177, v44, v45
	v_cvt_pk_bf16_f32 v178, v46, v47
	v_cvt_pk_bf16_f32 v179, v48, v49
	s_nop 1
	ds_read2_b64 v[180:183], v138 offset0:164 offset1:166
	ds_read2_b64 v[252:255], v175 offset0:136 offset1:138
	ds_read2_b64 v[42:45], v138 offset0:168 offset1:170
	s_waitcnt lgkmcnt(3)
	v_mfma_f32_32x32x16_bf16 v[2:17], v[38:41], v[176:179], v[2:17]
	s_waitcnt lgkmcnt(2)
	v_mfma_f32_32x32x16_bf16 v[18:33], v[180:183], v[176:179], v[18:33]
	v_cvt_pk_bf16_f32 v176, v50, v51
	v_cvt_pk_bf16_f32 v177, v52, v53
	v_cvt_pk_bf16_f32 v178, v54, v55
	v_cvt_pk_bf16_f32 v179, v56, v57
	s_nop 1
	ds_read2_b64 v[38:41], v175 offset0:140 offset1:142
	ds_read2_b64 v[180:183], v138 offset0:172 offset1:174
	s_waitcnt lgkmcnt(3)
	v_mfma_f32_32x32x16_bf16 v[2:17], v[252:255], v[176:179], v[2:17]
	s_waitcnt lgkmcnt(2)
	v_mfma_f32_32x32x16_bf16 v[18:33], v[42:45], v[176:179], v[18:33]
	v_cvt_pk_bf16_f32 v176, v58, v59
	v_cvt_pk_bf16_f32 v177, v60, v61
	v_cvt_pk_bf16_f32 v178, v62, v63
	v_cvt_pk_bf16_f32 v179, v64, v65
	s_nop 1
	s_waitcnt lgkmcnt(1)
	v_mfma_f32_32x32x16_bf16 v[2:17], v[38:41], v[176:179], v[2:17]
	s_waitcnt lgkmcnt(0)
	v_mfma_f32_32x32x16_bf16 v[18:33], v[180:183], v[176:179], v[18:33]
	s_setprio 0
	s_andn2_b64 vcc, exec, s[46:47]
	s_cbranch_vccnz .LBB0_1853
	s_waitcnt lgkmcnt(0)
	s_barrier
	s_cmp_gt_i32 s3, s5
	s_cbranch_scc1 .LBB0_1838
	v_add3_u32 v138, s0, v207, v198
	s_waitcnt vmcnt(1)
	ds_write_b128 v138, v[114:117]
	v_add_u32_e32 v138, s0, v208
	v_add3_u32 v138, v138, v198, s13
	s_cmp_gt_i32 s3, s27
	s_waitcnt vmcnt(0)
	ds_write2_b64 v138, v[118:119], v[120:121] offset1:1
	s_cbranch_scc1 .LBB0_1838
	s_add_i32 s0, s26, s4
	s_add_i32 s34, s0, 64
	v_lshl_add_u64 v[114:115], v[130:131], 0, v[198:199]
	v_lshl_add_u64 v[118:119], s[34:35], 1, v[132:133]
	global_load_dwordx4 v[114:117], v[114:115], off
	s_nop 0
	global_load_dwordx4 v[118:121], v[118:119], off offset:384

; #define LAS __attribute__((address_space(3)))
; #define MFMA32(a, b, c) __builtin_amdgcn_mfma_f32_32x32x16_bf16((a), (b), (c), 0, 0, 0)
; #define NSA_PRIO_ON(c) do { if ((c).hiw) __builtin_amdgcn_s_setprio(3); else __builtin_amdgcn_s_setprio(1); } while (0)
; #define NSA_PRIO_OFF() __builtin_amdgcn_s_setprio(0)
; template <int BR> __device__ __forceinline__ void nsa_s_tile(LAS unsigned char* L, int slot, const NsaBr& c, const bf16x8 (&qr)[4], f32x16 (&sa)[2]) {
;     NSA_PRIO_ON(c);
; #pragma unroll
;     for (int kt = 0; kt < 2; ++kt) {
; #pragma unroll
;         for (int i = 0; i < 16; ++i) sa[kt][i] = 0.f;
; #pragma unroll
;         for (int ks = 0; ks < 4; ++ks) { const bf16x8 a = *(const LAS bf16x8*)(L + slot + (32 * kt + c.r) * 144 + (16 * ks + 8 * c.h) * 2); sa[kt] = MFMA32(a, qr[ks], sa[kt]); }
;     }
;     NSA_PRIO_OFF();
; }
.LBB0_1843:
	v_add_u32_e32 v138, s49, v209
	ds_read_b128 v[34:37], v138
	ds_read_b128 v[54:57], v138 offset:32
	ds_read_b128 v[58:61], v138 offset:64
	ds_read_b128 v[62:65], v138 offset:96
	ds_read_b128 v[50:53], v138 offset:4608
	ds_read_b128 v[176:179], v138 offset:4640
	ds_read_b128 v[252:255], v138 offset:4672
	s_waitcnt lgkmcnt(6)
	v_mfma_f32_32x32x16_bf16 v[34:49], v[34:37], v[98:101], 0
	s_waitcnt lgkmcnt(5)
	v_mfma_f32_32x32x16_bf16 v[34:49], v[54:57], v[102:105], v[34:49]
	s_waitcnt lgkmcnt(4)
	v_mfma_f32_32x32x16_bf16 v[34:49], v[58:61], v[106:109], v[34:49]
	s_waitcnt lgkmcnt(3)
	v_mfma_f32_32x32x16_bf16 v[34:49], v[62:65], v[110:113], v[34:49]
	s_waitcnt lgkmcnt(2)
	v_mfma_f32_32x32x16_bf16 v[50:65], v[50:53], v[98:101], 0
	s_waitcnt lgkmcnt(1)
	v_mfma_f32_32x32x16_bf16 v[50:65], v[176:179], v[102:105], v[50:65]
	ds_read_b128 v[176:179], v138 offset:4704
	s_waitcnt lgkmcnt(1)
	v_mfma_f32_32x32x16_bf16 v[50:65], v[252:255], v[106:109], v[50:65]
	s_waitcnt lgkmcnt(0)
	v_mfma_f32_32x32x16_bf16 v[50:65], v[176:179], v[110:113], v[50:65]
	s_setprio 0
	s_cmp_eq_u32 s48, s4
	s_mov_b64 s[0:1], -1
	s_cbranch_scc0 .LBB0_1856

; #define LAS __attribute__((address_space(3)))
; #define MFMA32(a, b, c) __builtin_amdgcn_mfma_f32_32x32x16_bf16((a), (b), (c), 0, 0, 0)
; #define NSA_PRIO_ON(c) do { if ((c).hiw) __builtin_amdgcn_s_setprio(3); else __builtin_amdgcn_s_setprio(1); } while (0)
; #define NSA_PRIO_OFF() __builtin_amdgcn_s_setprio(0)
; template <int BR> __device__ __forceinline__ void nsa_softmax_pv(LAS unsigned char* L, int slot, const NsaBr& c, int j, f32x16 (&sa)[2], f32x16 (&oacc)[2], float& mrun, float& lrun) {
;     ...
;     const float msub = (BR == 1 && !mine) ? 1e30f : mrun;
;     f32x2 ps2 = {0.f, 0.f}; float nmsub = -msub; asm volatile("" : "+v"(nmsub)); const f32x2 nm2 = {nmsub, nmsub};
; #pragma unroll
;     for (int kt = 0; kt < 2; ++kt) {
; #pragma unroll
;         for (int i = 0; i < 16; i += 2) { const f32x2 x = (f32x2){sa[kt][i], sa[kt][i + 1]} + nm2; sa[kt][i] = __builtin_amdgcn_exp2f(x.x); sa[kt][i + 1] = __builtin_amdgcn_exp2f(x.y); }
; #pragma unroll
;         for (int i = 0; i < 16; i += 2) ps2 += (f32x2){sa[kt][i], sa[kt][i + 1]};
;     }
;     const float psum = ps2.x + ps2.y;
;     lrun += psum;
;     NSA_PRIO_ON(c);
; #pragma unroll
;     for (int kt = 0; kt < 2; ++kt)
; #pragma unroll
;         for (int s2 = 0; s2 < 2; ++s2) { const bf16x8 pf = pack_step(sa[kt], s2);
; #pragma unroll
;             for (int dt = 0; dt < 2; ++dt) { const LAS unsigned char* vp = L + slot + 9216 + (32 * dt + r) * 136 + (32 * kt + 16 * s2 + 4 * h) * 2;
;                 const s16x4 lo = *(const LAS s16x4*)vp, hi = *(const LAS s16x4*)(vp + 16);
;                 const bf16x8 vf = __builtin_shufflevector(lo, hi, 0, 1, 2, 3, 4, 5, 6, 7);
;                 oacc[dt] = MFMA32(vf, pf, oacc[dt]); } }
;     NSA_PRIO_OFF();
.LBB0_1852:
	v_pk_add_f32 v[66:67], v[66:67], v[122:123] op_sel_hi:[1,0]
	v_pk_add_f32 v[68:69], v[68:69], v[122:123] op_sel_hi:[1,0]
	v_exp_f32_e32 v66, v66
	v_exp_f32_e32 v67, v67
	v_exp_f32_e32 v68, v68
	v_exp_f32_e32 v69, v69
	v_pk_add_f32 v[70:71], v[70:71], v[122:123] op_sel_hi:[1,0]
	v_pk_add_f32 v[72:73], v[72:73], v[122:123] op_sel_hi:[1,0]
	v_exp_f32_e32 v70, v70
	v_exp_f32_e32 v71, v71
	v_exp_f32_e32 v72, v72
	v_exp_f32_e32 v73, v73
	v_pk_add_f32 v[74:75], v[74:75], v[122:123] op_sel_hi:[1,0]
	v_pk_add_f32 v[76:77], v[76:77], v[122:123] op_sel_hi:[1,0]
	v_exp_f32_e32 v74, v74
	v_exp_f32_e32 v75, v75
	v_pk_add_f32 v[176:177], v[66:67], 0 op_sel_hi:[1,0]
	v_exp_f32_e32 v76, v76
	v_exp_f32_e32 v77, v77
	v_pk_add_f32 v[78:79], v[78:79], v[122:123] op_sel_hi:[1,0]
	v_pk_add_f32 v[176:177], v[68:69], v[176:177]
	v_exp_f32_e32 v78, v78
	v_exp_f32_e32 v79, v79
	v_pk_add_f32 v[80:81], v[80:81], v[122:123] op_sel_hi:[1,0]
	v_pk_add_f32 v[176:177], v[70:71], v[176:177]
	v_exp_f32_e32 v80, v80
	v_exp_f32_e32 v81, v81
	v_pk_add_f32 v[176:177], v[72:73], v[176:177]
	v_pk_add_f32 v[82:83], v[82:83], v[122:123] op_sel_hi:[1,0]
	v_pk_add_f32 v[176:177], v[74:75], v[176:177]
	v_exp_f32_e32 v82, v82
	v_exp_f32_e32 v83, v83
	v_pk_add_f32 v[84:85], v[84:85], v[122:123] op_sel_hi:[1,0]
	v_pk_add_f32 v[176:177], v[76:77], v[176:177]
	v_exp_f32_e32 v84, v84
	v_exp_f32_e32 v85, v85
	v_pk_add_f32 v[86:87], v[86:87], v[122:123] op_sel_hi:[1,0]
	v_pk_add_f32 v[176:177], v[78:79], v[176:177]
	v_exp_f32_e32 v86, v86
	v_exp_f32_e32 v87, v87
	v_pk_add_f32 v[88:89], v[88:89], v[122:123] op_sel_hi:[1,0]
	v_pk_add_f32 v[176:177], v[80:81], v[176:177]
	v_exp_f32_e32 v88, v88
	v_exp_f32_e32 v89, v89
	v_pk_add_f32 v[90:91], v[90:91], v[122:123] op_sel_hi:[1,0]
	v_pk_add_f32 v[92:93], v[92:93], v[122:123] op_sel_hi:[1,0]
	v_exp_f32_e32 v90, v90
	v_exp_f32_e32 v91, v91
	v_pk_add_f32 v[176:177], v[82:83], v[176:177]
	v_exp_f32_e32 v92, v92
	v_exp_f32_e32 v93, v93
	v_pk_add_f32 v[94:95], v[94:95], v[122:123] op_sel_hi:[1,0]
	v_pk_add_f32 v[176:177], v[84:85], v[176:177]
	v_exp_f32_e32 v94, v94
	v_exp_f32_e32 v95, v95
	v_pk_add_f32 v[96:97], v[96:97], v[122:123] op_sel_hi:[1,0]
	v_pk_add_f32 v[176:177], v[86:87], v[176:177]
	v_exp_f32_e32 v96, v96
	v_exp_f32_e32 v97, v97
	v_pk_add_f32 v[176:177], v[88:89], v[176:177]
	s_nop 0
	v_pk_add_f32 v[176:177], v[90:91], v[176:177]
	s_nop 0
	v_pk_add_f32 v[176:177], v[92:93], v[176:177]
	s_nop 0
	v_pk_add_f32 v[176:177], v[94:95], v[176:177]
	s_nop 0
	v_pk_add_f32 v[176:177], v[96:97], v[176:177]
	s_nop 0
	v_add_f32_e32 v122, v176, v177
	v_add_f32_e32 v155, v155, v122
	v_add_u32_e32 v122, s50, v211
	v_add_u32_e32 v138, 0x2000, v122
	v_cvt_pk_bf16_f32 v176, v66, v67
	v_cvt_pk_bf16_f32 v177, v68, v69
	v_cvt_pk_bf16_f32 v178, v70, v71
	v_cvt_pk_bf16_f32 v179, v72, v73
	s_nop 1
	v_add_u32_e32 v122, 0x3000, v122
	ds_read2_b64 v[180:183], v138 offset0:128 offset1:130
	ds_read2_b64 v[252:255], v122 offset0:160 offset1:162
	ds_read2_b64 v[70:73], v138 offset0:132 offset1:134
	s_waitcnt lgkmcnt(2)
	v_mfma_f32_32x32x16_bf16 v[2:17], v[180:183], v[176:179], v[2:17]
	s_waitcnt lgkmcnt(1)
	v_mfma_f32_32x32x16_bf16 v[18:33], v[252:255], v[176:179], v[18:33]
	v_cvt_pk_bf16_f32 v176, v74, v75
	v_cvt_pk_bf16_f32 v177, v76, v77
	v_cvt_pk_bf16_f32 v178, v78, v79
	v_cvt_pk_bf16_f32 v179, v80, v81
	s_nop 1
	ds_read2_b64 v[180:183], v122 offset0:164 offset1:166
	ds_read2_b64 v[252:255], v138 offset0:136 offset1:138
	ds_read2_b64 v[74:77], v122 offset0:168 offset1:170
	s_waitcnt lgkmcnt(3)
	v_mfma_f32_32x32x16_bf16 v[2:17], v[70:73], v[176:179], v[2:17]
	s_waitcnt lgkmcnt(2)
	v_mfma_f32_32x32x16_bf16 v[18:33], v[180:183], v[176:179], v[18:33]
	v_cvt_pk_bf16_f32 v176, v82, v83
	v_cvt_pk_bf16_f32 v177, v84, v85
	v_cvt_pk_bf16_f32 v178, v86, v87
	v_cvt_pk_bf16_f32 v179, v88, v89
	s_nop 1
	ds_read2_b64 v[70:73], v138 offset0:140 offset1:142
	ds_read2_b64 v[180:183], v122 offset0:172 offset1:174
	s_waitcnt lgkmcnt(3)
	v_mfma_f32_32x32x16_bf16 v[2:17], v[252:255], v[176:179], v[2:17]
	s_waitcnt lgkmcnt(2)
	v_mfma_f32_32x32x16_bf16 v[18:33], v[74:77], v[176:179], v[18:33]
	v_cvt_pk_bf16_f32 v176, v90, v91
	v_cvt_pk_bf16_f32 v177, v92, v93
	v_cvt_pk_bf16_f32 v178, v94, v95
	v_cvt_pk_bf16_f32 v179, v96, v97
	s_nop 1
	s_waitcnt lgkmcnt(1)
	v_mfma_f32_32x32x16_bf16 v[2:17], v[70:73], v[176:179], v[2:17]
	s_waitcnt lgkmcnt(0)
	v_mfma_f32_32x32x16_bf16 v[18:33], v[180:183], v[176:179], v[18:33]
	s_setprio 0

; template <int BR> __device__ __forceinline__ void nsa_softmax_pv(LAS unsigned char* L, int slot, const NsaBr& c, int j, f32x16 (&sa)[2], f32x16 (&oacc)[2], float& mrun, float& lrun) {
;     ...
; #pragma unroll
;         for (int kt = 0; kt < 2; ++kt)
; #pragma unroll
;             for (int i = 0; i < 16; i += 2) mblk = fmaxf(mblk, fmaxf(sa[kt][i], sa[kt][i + 1]));
;     }
.LBB0_1856:
	v_max3_f32 v138, v66, s12, v67
	v_max3_f32 v138, v138, v68, v69
	v_max3_f32 v138, v138, v70, v71
	v_max3_f32 v138, v138, v72, v73
	v_max3_f32 v138, v138, v74, v75
	v_max3_f32 v138, v138, v76, v77
	v_max3_f32 v138, v138, v78, v79
	v_max3_f32 v138, v138, v80, v81
	v_max3_f32 v138, v138, v82, v83
	v_max3_f32 v138, v138, v84, v85
	v_max3_f32 v138, v138, v86, v87
	v_max3_f32 v138, v138, v88, v89
	v_max3_f32 v138, v138, v90, v91
	v_max3_f32 v138, v138, v92, v93
	v_max3_f32 v138, v138, v94, v95
	v_max3_f32 v138, v138, v96, v97
	s_cbranch_execz .LBB0_1845
	s_branch .LBB0_1846

; #define LAS __attribute__((address_space(3)))
; #define GAS __attribute__((address_space(1)))
; __global__ void __launch_bounds__(NTHR, 2) fwd(Args args) {
;     extern __shared__ __attribute__((aligned(16))) unsigned char lds_raw[];
;     Frame F;
;     F.lds = (LAS unsigned char*)lds_raw; F.ws = (GAS unsigned char*)args.ws; F.out = (GAS float*)args.out; F.in = args.in;
;     F.tid = threadIdx.x; F.lane = F.tid & 63; F.wave = __builtin_amdgcn_readfirstlane(F.tid >> 6); F.bid = blockIdx.x; F.G = gridDim.x;
	.amdhsa_kernel _Z3fwd4Args
		.amdhsa_group_segment_fixed_size 0
		.amdhsa_private_segment_fixed_size 0
		.amdhsa_kernarg_size 440
		.amdhsa_user_sgpr_count 2
		.amdhsa_user_sgpr_dispatch_ptr 0
		.amdhsa_user_sgpr_queue_ptr 0
		.amdhsa_user_sgpr_kernarg_segment_ptr 1
		.amdhsa_user_sgpr_dispatch_id 0
		.amdhsa_user_sgpr_kernarg_preload_length 0
		.amdhsa_user_sgpr_kernarg_preload_offset 0
		.amdhsa_user_sgpr_private_segment_size 0
		.amdhsa_uses_dynamic_stack 0
		.amdhsa_enable_private_segment 0
		.amdhsa_system_sgpr_workgroup_id_x 1
		.amdhsa_system_sgpr_workgroup_id_y 0
		.amdhsa_system_sgpr_workgroup_id_z 0
		.amdhsa_system_sgpr_workgroup_info 0
		.amdhsa_system_vgpr_workitem_id 0
		.amdhsa_next_free_vgpr 256
		.amdhsa_next_free_sgpr 102
		.amdhsa_accum_offset 256
		.amdhsa_reserve_vcc 1
		.amdhsa_float_round_mode_32 0
		.amdhsa_float_round_mode_16_64 0
		.amdhsa_float_denorm_mode_32 3
		.amdhsa_float_denorm_mode_16_64 3
		.amdhsa_dx10_clamp 1
		.amdhsa_ieee_mode 1
		.amdhsa_fp16_overflow 0
		.amdhsa_tg_split 0
		.amdhsa_exception_fp_ieee_invalid_op 0
		.amdhsa_exception_fp_denorm_src 0
		.amdhsa_exception_fp_ieee_div_zero 0
		.amdhsa_exception_fp_ieee_overflow 0
		.amdhsa_exception_fp_ieee_underflow 0
		.amdhsa_exception_fp_ieee_inexact 0
		.amdhsa_exception_int_div_zero 0
	.end_amdhsa_kernel

; #define LAS __attribute__((address_space(3)))
; #define GAS __attribute__((address_space(1)))
; __global__ void __launch_bounds__(NTHR, 2) fwd(Args args) {
;     extern __shared__ __attribute__((aligned(16))) unsigned char lds_raw[];
;     Frame F;
;     F.lds = (LAS unsigned char*)lds_raw; F.ws = (GAS unsigned char*)args.ws; F.out = (GAS float*)args.out; F.in = args.in;
;     F.tid = threadIdx.x; F.lane = F.tid & 63; F.wave = __builtin_amdgcn_readfirstlane(F.tid >> 6); F.bid = blockIdx.x; F.G = gridDim.x;
amdhsa.kernels:
  - .agpr_count:     0
    .args:
      - .offset:         0
        .size:           184
        .value_kind:     by_value
      - .offset:         184
        .size:           4
        .value_kind:     hidden_block_count_x
      - .offset:         188
        .size:           4
        .value_kind:     hidden_block_count_y
      - .offset:         192
        .size:           4
        .value_kind:     hidden_block_count_z
      - .offset:         196
        .size:           2
        .value_kind:     hidden_group_size_x
      - .offset:         198
        .size:           2
        .value_kind:     hidden_group_size_y
      - .offset:         200
        .size:           2
        .value_kind:     hidden_group_size_z
      - .offset:         202
        .size:           2
        .value_kind:     hidden_remainder_x
      - .offset:         204
        .size:           2
        .value_kind:     hidden_remainder_y
      - .offset:         206
        .size:           2
        .value_kind:     hidden_remainder_z
      - .offset:         224
        .size:           8
        .value_kind:     hidden_global_offset_x
      - .offset:         232
        .size:           8
        .value_kind:     hidden_global_offset_y
      - .offset:         240
        .size:           8
        .value_kind:     hidden_global_offset_z
      - .offset:         248
        .size:           2
        .value_kind:     hidden_grid_dims
      - .offset:         304
        .size:           4
        .value_kind:     hidden_dynamic_lds_size
    .group_segment_fixed_size: 0
    .kernarg_segment_align: 8
    .kernarg_segment_size: 440
    .language:       OpenCL C
    .language_version:
      - 2
      - 0
    .max_flat_workgroup_size: 512
    .name:           _Z3fwd4Args
    .private_segment_fixed_size: 0
    .sgpr_count:     108
    .sgpr_spill_count: 273
    .symbol:         _Z3fwd4Args.kd
    .uniform_work_group_size: 1
    .uses_dynamic_stack: false
    .vgpr_count:     256
    .vgpr_spill_count: 0
    .wavefront_size: 64
